# GEMM phases: next-tile accumulators cleared with 64 v_mov_b64 instead of 128 v_mov_b32
# speedup vs baseline: 1.0158x; 1.0006x over previous
.LBB0_278:
	s_ashr_i32 s19, s18, 31
	s_lshl_b64 s[22:23], s[18:19], 11
	s_add_u32 s22, s2, s22
	s_addc_u32 s23, s20, s23
	s_and_b64 s[24:25], s[4:5], exec
	s_cselect_b32 s19, s23, s7
	s_cselect_b32 s49, s22, s6
	s_ashr_i32 s17, s16, 31
	s_lshl_b64 s[24:25], s[16:17], 19
	s_add_u32 s24, s21, s24
	s_addc_u32 s25, s30, s25
	s_and_b64 s[28:29], s[4:5], exec
	s_cselect_b32 s17, s25, s27
	s_cselect_b32 s50, s24, s26
	s_add_u32 s6, s6, 0x40080
	s_addc_u32 s7, s7, 0
	s_add_u32 s51, s26, 0x100
	s_addc_u32 s52, s27, 0
	s_mov_b32 s53, -2
	v_mov_b64_e32 v[0:1], 0
	v_mov_b64_e32 v[2:3], 0
	v_mov_b64_e32 v[4:5], 0
	v_mov_b64_e32 v[6:7], 0
	v_mov_b64_e32 v[8:9], 0
	v_mov_b64_e32 v[10:11], 0
	v_mov_b64_e32 v[12:13], 0
	v_mov_b64_e32 v[14:15], 0
	v_mov_b64_e32 v[16:17], 0
	v_mov_b64_e32 v[18:19], 0
	v_mov_b64_e32 v[20:21], 0
	v_mov_b64_e32 v[22:23], 0
	v_mov_b64_e32 v[24:25], 0
	v_mov_b64_e32 v[26:27], 0
	v_mov_b64_e32 v[28:29], 0
	v_mov_b64_e32 v[30:31], 0
	v_mov_b64_e32 v[32:33], 0
	v_mov_b64_e32 v[34:35], 0
	v_mov_b64_e32 v[36:37], 0
	v_mov_b64_e32 v[38:39], 0
	v_mov_b64_e32 v[40:41], 0
	v_mov_b64_e32 v[42:43], 0
	v_mov_b64_e32 v[44:45], 0
	v_mov_b64_e32 v[46:47], 0
	v_mov_b64_e32 v[48:49], 0
	v_mov_b64_e32 v[50:51], 0
	v_mov_b64_e32 v[52:53], 0
	v_mov_b64_e32 v[54:55], 0
	v_mov_b64_e32 v[56:57], 0
	v_mov_b64_e32 v[58:59], 0
	v_mov_b64_e32 v[60:61], 0
	v_mov_b64_e32 v[62:63], 0
	v_mov_b64_e32 v[64:65], 0
	v_mov_b64_e32 v[66:67], 0
	v_mov_b64_e32 v[68:69], 0
	v_mov_b64_e32 v[70:71], 0
	v_mov_b64_e32 v[72:73], 0
	v_mov_b64_e32 v[74:75], 0
	v_mov_b64_e32 v[76:77], 0
	v_mov_b64_e32 v[78:79], 0
	v_mov_b64_e32 v[80:81], 0
	v_mov_b64_e32 v[82:83], 0
	v_mov_b64_e32 v[84:85], 0
	v_mov_b64_e32 v[86:87], 0
	v_mov_b64_e32 v[88:89], 0
	v_mov_b64_e32 v[90:91], 0
	v_mov_b64_e32 v[92:93], 0
	v_mov_b64_e32 v[94:95], 0
	v_mov_b64_e32 v[96:97], 0
	v_mov_b64_e32 v[98:99], 0
	v_mov_b64_e32 v[100:101], 0
	v_mov_b64_e32 v[102:103], 0
	v_mov_b64_e32 v[104:105], 0
	v_mov_b64_e32 v[106:107], 0
	v_mov_b64_e32 v[108:109], 0
	v_mov_b64_e32 v[110:111], 0
	v_mov_b64_e32 v[112:113], 0
	v_mov_b64_e32 v[114:115], 0
	v_mov_b64_e32 v[116:117], 0
	v_mov_b64_e32 v[118:119], 0
	v_mov_b64_e32 v[120:121], 0
	v_mov_b64_e32 v[122:123], 0
	v_mov_b64_e32 v[124:125], 0
	v_mov_b64_e32 v[126:127], 0
	v_lshl_add_u32 v138, s47, 8, v146
	v_ashrrev_i32_e32 v139, 31, v138
	v_lshl_add_u64 v[144:145], v[138:139], 2, s[12:13]
	global_load_dword v234, v[144:145], off
	global_load_dword v235, v[144:145], off offset:64
	global_load_dword v236, v[144:145], off offset:128
	global_load_dword v237, v[144:145], off offset:192
	global_load_dword v238, v[144:145], off offset:512
	global_load_dword v239, v[144:145], off offset:576
	global_load_dword v240, v[144:145], off offset:640
	global_load_dword v241, v[144:145], off offset:704

.LBB0_643:
	s_ashr_i32 s23, s22, 31
	s_lshl_b64 s[24:25], s[22:23], 11
	s_add_u32 s24, s8, s24
	s_addc_u32 s25, s9, s25
	s_and_b64 s[26:27], s[6:7], exec
	s_cselect_b32 s23, s25, s31
	s_cselect_b32 s29, s24, s30
	s_ashr_i32 s19, s18, 31
	s_lshl_b64 s[26:27], s[18:19], 19
	s_add_u32 s26, s20, s26
	s_addc_u32 s27, s21, s27
	s_and_b64 s[36:37], s[6:7], exec
	s_cselect_b32 s19, s27, s35
	s_cselect_b32 s53, s26, s34
	s_add_u32 s30, s30, 0x40080
	s_addc_u32 s31, s31, 0
	s_add_u32 s54, s34, 0x100
	s_addc_u32 s55, s35, 0
	s_mov_b32 s56, -2
	s_waitcnt lgkmcnt(0)
	v_mov_b64_e32 v[0:1], 0
	v_mov_b64_e32 v[2:3], 0
	v_mov_b64_e32 v[4:5], 0
	v_mov_b64_e32 v[6:7], 0
	v_mov_b64_e32 v[8:9], 0
	v_mov_b64_e32 v[10:11], 0
	v_mov_b64_e32 v[12:13], 0
	v_mov_b64_e32 v[14:15], 0
	v_mov_b64_e32 v[16:17], 0
	v_mov_b64_e32 v[18:19], 0
	v_mov_b64_e32 v[20:21], 0
	v_mov_b64_e32 v[22:23], 0
	v_mov_b64_e32 v[24:25], 0
	v_mov_b64_e32 v[26:27], 0
	v_mov_b64_e32 v[28:29], 0
	v_mov_b64_e32 v[30:31], 0
	v_mov_b64_e32 v[32:33], 0
	v_mov_b64_e32 v[34:35], 0
	v_mov_b64_e32 v[36:37], 0
	v_mov_b64_e32 v[38:39], 0
	v_mov_b64_e32 v[40:41], 0
	v_mov_b64_e32 v[42:43], 0
	v_mov_b64_e32 v[44:45], 0
	v_mov_b64_e32 v[46:47], 0
	v_mov_b64_e32 v[48:49], 0
	v_mov_b64_e32 v[50:51], 0
	v_mov_b64_e32 v[52:53], 0
	v_mov_b64_e32 v[54:55], 0
	v_mov_b64_e32 v[56:57], 0
	v_mov_b64_e32 v[58:59], 0
	v_mov_b64_e32 v[60:61], 0
	v_mov_b64_e32 v[62:63], 0
	v_mov_b64_e32 v[64:65], 0
	v_mov_b64_e32 v[66:67], 0
	v_mov_b64_e32 v[68:69], 0
	v_mov_b64_e32 v[70:71], 0
	v_mov_b64_e32 v[72:73], 0
	v_mov_b64_e32 v[74:75], 0
	v_mov_b64_e32 v[76:77], 0
	v_mov_b64_e32 v[78:79], 0
	v_mov_b64_e32 v[80:81], 0
	v_mov_b64_e32 v[82:83], 0
	v_mov_b64_e32 v[84:85], 0
	v_mov_b64_e32 v[86:87], 0
	v_mov_b64_e32 v[88:89], 0
	v_mov_b64_e32 v[90:91], 0
	v_mov_b64_e32 v[92:93], 0
	v_mov_b64_e32 v[94:95], 0
	v_mov_b64_e32 v[96:97], 0
	v_mov_b64_e32 v[98:99], 0
	v_mov_b64_e32 v[100:101], 0
	v_mov_b64_e32 v[102:103], 0
	v_mov_b64_e32 v[104:105], 0
	v_mov_b64_e32 v[106:107], 0
	v_mov_b64_e32 v[108:109], 0
	v_mov_b64_e32 v[110:111], 0
	v_mov_b64_e32 v[112:113], 0
	v_mov_b64_e32 v[114:115], 0
	v_mov_b64_e32 v[116:117], 0
	v_mov_b64_e32 v[118:119], 0
	v_mov_b64_e32 v[120:121], 0
	v_mov_b64_e32 v[122:123], 0
	v_mov_b64_e32 v[124:125], 0
	v_mov_b64_e32 v[126:127], 0

.LBB0_744:
	s_ashr_i32 s37, s36, 31
	s_lshl_b64 s[18:19], s[36:37], 11
	v_readlane_b32 s8, v242, 22
	s_add_u32 s42, s8, s18
	s_addc_u32 s43, s68, s19
	s_and_b64 s[18:19], s[46:47], exec
	s_cselect_b32 s23, s43, s15
	s_cselect_b32 s24, s42, s14
	s_ashr_i32 s35, s34, 31
	s_lshl_b64 s[18:19], s[34:35], 19
	s_add_u32 s44, s29, s18
	s_addc_u32 s45, s97, s19
	s_and_b64 s[18:19], s[46:47], exec
	s_cselect_b32 s25, s45, s17
	s_cselect_b32 s35, s44, s16
	s_add_u32 s14, s14, 0x3e080
	s_addc_u32 s15, s15, 0
	s_add_u32 s37, s16, 0x100
	s_addc_u32 s48, s17, 0
	s_mov_b32 s49, -2
	v_mov_b64_e32 v[0:1], 0
	v_mov_b64_e32 v[2:3], 0
	v_mov_b64_e32 v[4:5], 0
	v_mov_b64_e32 v[6:7], 0
	v_mov_b64_e32 v[8:9], 0
	v_mov_b64_e32 v[10:11], 0
	v_mov_b64_e32 v[12:13], 0
	v_mov_b64_e32 v[14:15], 0
	v_mov_b64_e32 v[16:17], 0
	v_mov_b64_e32 v[18:19], 0
	v_mov_b64_e32 v[20:21], 0
	v_mov_b64_e32 v[22:23], 0
	v_mov_b64_e32 v[24:25], 0
	v_mov_b64_e32 v[26:27], 0
	v_mov_b64_e32 v[28:29], 0
	v_mov_b64_e32 v[30:31], 0
	v_mov_b64_e32 v[32:33], 0
	v_mov_b64_e32 v[34:35], 0
	v_mov_b64_e32 v[36:37], 0
	v_mov_b64_e32 v[38:39], 0
	v_mov_b64_e32 v[40:41], 0
	v_mov_b64_e32 v[42:43], 0
	v_mov_b64_e32 v[44:45], 0
	v_mov_b64_e32 v[46:47], 0
	v_mov_b64_e32 v[48:49], 0
	v_mov_b64_e32 v[50:51], 0
	v_mov_b64_e32 v[52:53], 0
	v_mov_b64_e32 v[54:55], 0
	v_mov_b64_e32 v[56:57], 0
	v_mov_b64_e32 v[58:59], 0
	v_mov_b64_e32 v[60:61], 0
	v_mov_b64_e32 v[62:63], 0
	v_mov_b64_e32 v[64:65], 0
	v_mov_b64_e32 v[66:67], 0
	v_mov_b64_e32 v[68:69], 0
	v_mov_b64_e32 v[70:71], 0
	v_mov_b64_e32 v[72:73], 0
	v_mov_b64_e32 v[74:75], 0
	v_mov_b64_e32 v[76:77], 0
	v_mov_b64_e32 v[78:79], 0
	v_mov_b64_e32 v[96:97], 0
	v_mov_b64_e32 v[98:99], 0
	v_mov_b64_e32 v[100:101], 0
	v_mov_b64_e32 v[102:103], 0
	v_mov_b64_e32 v[104:105], 0
	v_mov_b64_e32 v[106:107], 0
	v_mov_b64_e32 v[112:113], 0
	v_mov_b64_e32 v[114:115], 0
	v_mov_b64_e32 v[128:129], 0
	v_mov_b64_e32 v[130:131], 0
	v_mov_b64_e32 v[132:133], 0
	v_mov_b64_e32 v[134:135], 0
	v_mov_b64_e32 v[136:137], 0
	v_mov_b64_e32 v[138:139], 0
	v_mov_b64_e32 v[140:141], 0
	v_mov_b64_e32 v[142:143], 0
	v_mov_b64_e32 v[144:145], 0
	v_mov_b64_e32 v[146:147], 0
	v_mov_b64_e32 v[148:149], 0
	v_mov_b64_e32 v[150:151], 0
	v_mov_b64_e32 v[152:153], 0
	v_mov_b64_e32 v[154:155], 0
	v_mov_b64_e32 v[156:157], 0
	v_mov_b64_e32 v[158:159], 0

.LBB0_926:
	s_add_u32 s51, s24, 0x100
	s_addc_u32 s52, s25, 0
	s_mov_b32 s53, -2
	v_mov_b64_e32 v[0:1], 0
	v_mov_b64_e32 v[2:3], 0
	v_mov_b64_e32 v[4:5], 0
	v_mov_b64_e32 v[6:7], 0
	v_mov_b64_e32 v[8:9], 0
	v_mov_b64_e32 v[10:11], 0
	v_mov_b64_e32 v[12:13], 0
	v_mov_b64_e32 v[14:15], 0
	v_mov_b64_e32 v[16:17], 0
	v_mov_b64_e32 v[18:19], 0
	v_mov_b64_e32 v[20:21], 0
	v_mov_b64_e32 v[22:23], 0
	v_mov_b64_e32 v[24:25], 0
	v_mov_b64_e32 v[26:27], 0
	v_mov_b64_e32 v[28:29], 0
	v_mov_b64_e32 v[30:31], 0
	v_mov_b64_e32 v[32:33], 0
	v_mov_b64_e32 v[34:35], 0
	v_mov_b64_e32 v[36:37], 0
	v_mov_b64_e32 v[38:39], 0
	v_mov_b64_e32 v[40:41], 0
	v_mov_b64_e32 v[42:43], 0
	v_mov_b64_e32 v[44:45], 0
	v_mov_b64_e32 v[46:47], 0
	v_mov_b64_e32 v[48:49], 0
	v_mov_b64_e32 v[50:51], 0
	v_mov_b64_e32 v[52:53], 0
	v_mov_b64_e32 v[54:55], 0
	v_mov_b64_e32 v[56:57], 0
	v_mov_b64_e32 v[58:59], 0
	v_mov_b64_e32 v[60:61], 0
	v_mov_b64_e32 v[62:63], 0
	v_mov_b64_e32 v[64:65], 0
	v_mov_b64_e32 v[66:67], 0
	v_mov_b64_e32 v[68:69], 0
	v_mov_b64_e32 v[70:71], 0
	v_mov_b64_e32 v[72:73], 0
	v_mov_b64_e32 v[74:75], 0
	v_mov_b64_e32 v[76:77], 0
	v_mov_b64_e32 v[78:79], 0
	v_mov_b64_e32 v[80:81], 0
	v_mov_b64_e32 v[82:83], 0
	v_mov_b64_e32 v[84:85], 0
	v_mov_b64_e32 v[86:87], 0
	v_mov_b64_e32 v[88:89], 0
	v_mov_b64_e32 v[90:91], 0
	v_mov_b64_e32 v[92:93], 0
	v_mov_b64_e32 v[94:95], 0
	v_mov_b64_e32 v[96:97], 0
	v_mov_b64_e32 v[98:99], 0
	v_mov_b64_e32 v[100:101], 0
	v_mov_b64_e32 v[102:103], 0
	v_mov_b64_e32 v[104:105], 0
	v_mov_b64_e32 v[106:107], 0
	v_mov_b64_e32 v[108:109], 0
	v_mov_b64_e32 v[110:111], 0
	v_mov_b64_e32 v[112:113], 0
	v_mov_b64_e32 v[114:115], 0
	v_mov_b64_e32 v[116:117], 0
	v_mov_b64_e32 v[118:119], 0
	v_mov_b64_e32 v[120:121], 0
	v_mov_b64_e32 v[122:123], 0
	v_mov_b64_e32 v[124:125], 0
	v_mov_b64_e32 v[126:127], 0

.LBB0_950:
	s_add_u32 s51, s24, 0x100
	s_addc_u32 s52, s25, 0
	s_mov_b32 s53, -2
	s_waitcnt lgkmcnt(0)
	v_mov_b64_e32 v[0:1], 0
	v_mov_b64_e32 v[2:3], 0
	v_mov_b64_e32 v[4:5], 0
	v_mov_b64_e32 v[6:7], 0
	v_mov_b64_e32 v[8:9], 0
	v_mov_b64_e32 v[10:11], 0
	v_mov_b64_e32 v[12:13], 0
	v_mov_b64_e32 v[14:15], 0
	v_mov_b64_e32 v[16:17], 0
	v_mov_b64_e32 v[18:19], 0
	v_mov_b64_e32 v[20:21], 0
	v_mov_b64_e32 v[22:23], 0
	v_mov_b64_e32 v[24:25], 0
	v_mov_b64_e32 v[26:27], 0
	v_mov_b64_e32 v[28:29], 0
	v_mov_b64_e32 v[30:31], 0
	v_mov_b64_e32 v[32:33], 0
	v_mov_b64_e32 v[34:35], 0
	v_mov_b64_e32 v[36:37], 0
	v_mov_b64_e32 v[38:39], 0
	v_mov_b64_e32 v[40:41], 0
	v_mov_b64_e32 v[42:43], 0
	v_mov_b64_e32 v[44:45], 0
	v_mov_b64_e32 v[46:47], 0
	v_mov_b64_e32 v[48:49], 0
	v_mov_b64_e32 v[50:51], 0
	v_mov_b64_e32 v[52:53], 0
	v_mov_b64_e32 v[54:55], 0
	v_mov_b64_e32 v[56:57], 0
	v_mov_b64_e32 v[58:59], 0
	v_mov_b64_e32 v[60:61], 0
	v_mov_b64_e32 v[62:63], 0
	v_mov_b64_e32 v[64:65], 0
	v_mov_b64_e32 v[66:67], 0
	v_mov_b64_e32 v[68:69], 0
	v_mov_b64_e32 v[70:71], 0
	v_mov_b64_e32 v[72:73], 0
	v_mov_b64_e32 v[74:75], 0
	v_mov_b64_e32 v[76:77], 0
	v_mov_b64_e32 v[78:79], 0
	v_mov_b64_e32 v[80:81], 0
	v_mov_b64_e32 v[82:83], 0
	v_mov_b64_e32 v[84:85], 0
	v_mov_b64_e32 v[86:87], 0
	v_mov_b64_e32 v[88:89], 0
	v_mov_b64_e32 v[90:91], 0
	v_mov_b64_e32 v[92:93], 0
	v_mov_b64_e32 v[94:95], 0
	v_mov_b64_e32 v[96:97], 0
	v_mov_b64_e32 v[98:99], 0
	v_mov_b64_e32 v[100:101], 0
	v_mov_b64_e32 v[102:103], 0
	v_mov_b64_e32 v[104:105], 0
	v_mov_b64_e32 v[106:107], 0
	v_mov_b64_e32 v[108:109], 0
	v_mov_b64_e32 v[110:111], 0
	v_mov_b64_e32 v[112:113], 0
	v_mov_b64_e32 v[114:115], 0
	v_mov_b64_e32 v[116:117], 0
	v_mov_b64_e32 v[118:119], 0
	v_mov_b64_e32 v[120:121], 0
	v_mov_b64_e32 v[122:123], 0
	v_mov_b64_e32 v[124:125], 0
	v_mov_b64_e32 v[126:127], 0
